# attention inner loops hand-scheduled: bulk LDS fragment prefetch, scalar f32 softmax ops, mid-iteration K/V staging one tile ahead
# speedup vs baseline: 1.0132x; 1.0132x over previous
.LBB0_455:
	s_add_i32 s29, s80, 1
	s_cmp_lt_i32 s29, s23
	s_cselect_b64 s[26:27], -1, 0
	s_cmp_ge_i32 s29, s23
	s_cbranch_scc1 .LBB0_457
	s_cmp_lg_u32 s80, 0
	s_cbranch_scc1 .LBB0_457
	s_cmp_gt_u32 s80, 6
	s_cselect_b64 vcc, -1, 0
	s_and_b64 vcc, s[24:25], vcc
	s_and_b64 vcc, vcc, exec
	s_cselect_b32 s39, s28, 0
	s_add_i32 s39, s39, s80
	s_add_i32 vcc_lo, s39, 1
	s_ashr_i32 vcc_hi, vcc_lo, 31
	s_lshl_b64 s[68:69], vcc, 13
	v_lshl_add_u64 v[34:35], v[92:93], 0, s[68:69]
	s_lshl_b64 s[68:69], vcc, 7
	global_load_dwordx4 v[82:85], v[34:35], off
	v_lshl_add_u64 v[34:35], v[90:91], 0, s[68:69]
	global_load_dwordx4 v[86:89], v[34:35], off
.LBB0_457:
	s_and_b32 s39, s80, 1
	s_mul_i32 s68, s39, 0x4800
	v_add_u32_e32 v0, s68, v95
	ds_read_b128 v[186:189], v0
	ds_read_b128 v[230:233], v0 offset:4608
	ds_read_b128 v[190:193], v0 offset:32
	ds_read_b128 v[234:237], v0 offset:4640
	ds_read_b128 v[194:197], v0 offset:64
	ds_read_b128 v[238:241], v0 offset:4672
	ds_read_b128 v[198:201], v0 offset:96
	ds_read_b128 v[242:245], v0 offset:4704
	s_cmp_lt_u32 s80, 8
	s_cselect_b64 s[68:69], -1, 0
	s_xor_b64 s[80:81], s[24:25], -1
	s_or_b64 s[68:69], s[80:81], s[68:69]
	s_waitcnt lgkmcnt(7)
	v_mfma_f32_32x32x16_bf16 v[34:49], v[186:189], v[66:69], 0
	s_waitcnt lgkmcnt(6)
	v_mfma_f32_32x32x16_bf16 v[50:65], v[230:233], v[66:69], 0
	s_waitcnt lgkmcnt(5)
	v_mfma_f32_32x32x16_bf16 v[34:49], v[190:193], v[70:73], v[34:49]
	s_waitcnt lgkmcnt(4)
	v_mfma_f32_32x32x16_bf16 v[50:65], v[234:237], v[70:73], v[50:65]
	s_waitcnt lgkmcnt(3)
	v_mfma_f32_32x32x16_bf16 v[34:49], v[194:197], v[74:77], v[34:49]
	s_waitcnt lgkmcnt(2)
	v_mfma_f32_32x32x16_bf16 v[50:65], v[238:241], v[74:77], v[50:65]
	s_waitcnt lgkmcnt(1)
	v_mfma_f32_32x32x16_bf16 v[34:49], v[198:201], v[78:81], v[34:49]
	s_waitcnt lgkmcnt(0)
	v_mfma_f32_32x32x16_bf16 v[50:65], v[242:245], v[78:81], v[50:65]
	ds_read_b128 v[96:99], v0 offset:9216
	ds_read_b128 v[118:121], v0 offset:13824
	ds_read_b128 v[100:103], v0 offset:9248
	ds_read_b128 v[122:125], v0 offset:13856
	ds_read_b128 v[104:107], v0 offset:9280
	ds_read_b128 v[126:129], v0 offset:13888
	ds_read_b128 v[108:111], v0 offset:9312
	ds_read_b128 v[246:249], v0 offset:13920
	s_and_b64 vcc, exec, s[68:69]
	s_cbranch_vccnz .LBB0_459
	v_cmp_lt_u32_e32 vcc, s85, v117
	v_add_u32_e32 v130, 32, v117
	s_nop 5
	v_cndmask_b32_e32 v34, v215, v34, vcc
	v_cmp_lt_u32_e32 vcc, s85, v130
	v_add_u32_e32 v130, 1, v117
	s_nop 0
	v_cndmask_b32_e32 v50, v215, v50, vcc
	v_cmp_lt_u32_e32 vcc, s85, v130
	v_add_u32_e32 v130, 33, v117
	s_nop 0
	v_cndmask_b32_e32 v35, v215, v35, vcc
	v_cmp_lt_u32_e32 vcc, s85, v130
	v_add_u32_e32 v130, 2, v117
	s_nop 0
	v_cndmask_b32_e32 v51, v215, v51, vcc
	v_cmp_lt_u32_e32 vcc, s85, v130
	v_add_u32_e32 v130, 34, v117
	s_nop 0
	v_cndmask_b32_e32 v36, v215, v36, vcc
	v_cmp_lt_u32_e32 vcc, s85, v130
	v_add_u32_e32 v130, 3, v117
	s_nop 0
	v_cndmask_b32_e32 v52, v215, v52, vcc
	v_cmp_lt_u32_e32 vcc, s85, v130
	v_add_u32_e32 v130, 35, v117
	s_nop 0
	v_cndmask_b32_e32 v37, v215, v37, vcc
	v_cmp_lt_u32_e32 vcc, s85, v130
	v_add_u32_e32 v130, 8, v117
	s_nop 0
	v_cndmask_b32_e32 v53, v215, v53, vcc
	v_cmp_lt_u32_e32 vcc, s85, v130
	v_add_u32_e32 v130, 40, v117
	s_nop 0
	v_cndmask_b32_e32 v38, v215, v38, vcc
	v_cmp_lt_u32_e32 vcc, s85, v130
	v_add_u32_e32 v130, 9, v117
	s_nop 0
	v_cndmask_b32_e32 v54, v215, v54, vcc
	v_cmp_lt_u32_e32 vcc, s85, v130
	v_add_u32_e32 v130, 41, v117
	s_nop 0
	v_cndmask_b32_e32 v39, v215, v39, vcc
	v_cmp_lt_u32_e32 vcc, s85, v130
	v_add_u32_e32 v130, 10, v117
	s_nop 0
	v_cndmask_b32_e32 v55, v215, v55, vcc
	v_cmp_lt_u32_e32 vcc, s85, v130
	v_add_u32_e32 v130, 42, v117
	s_nop 0
	v_cndmask_b32_e32 v40, v215, v40, vcc
	v_cmp_lt_u32_e32 vcc, s85, v130
	v_add_u32_e32 v130, 11, v117
	s_nop 0
	v_cndmask_b32_e32 v56, v215, v56, vcc
	v_cmp_lt_u32_e32 vcc, s85, v130
	v_add_u32_e32 v130, 43, v117
	s_nop 0
	v_cndmask_b32_e32 v41, v215, v41, vcc
	v_cmp_lt_u32_e32 vcc, s85, v130
	v_add_u32_e32 v130, 16, v117
	s_nop 0
	v_cndmask_b32_e32 v57, v215, v57, vcc
	v_cmp_lt_u32_e32 vcc, s85, v130
	v_add_u32_e32 v130, 48, v117
	s_nop 0
	v_cndmask_b32_e32 v42, v215, v42, vcc
	v_cmp_lt_u32_e32 vcc, s85, v130
	v_add_u32_e32 v130, 17, v117
	s_nop 0
	v_cndmask_b32_e32 v58, v215, v58, vcc
	v_cmp_lt_u32_e32 vcc, s85, v130
	v_add_u32_e32 v130, 49, v117
	s_nop 0
	v_cndmask_b32_e32 v43, v215, v43, vcc
	v_cmp_lt_u32_e32 vcc, s85, v130
	v_add_u32_e32 v130, 18, v117
	s_nop 0
	v_cndmask_b32_e32 v59, v215, v59, vcc
	v_cmp_lt_u32_e32 vcc, s85, v130
	v_add_u32_e32 v130, 50, v117
	s_nop 0
	v_cndmask_b32_e32 v44, v215, v44, vcc
	v_cmp_lt_u32_e32 vcc, s85, v130
	v_add_u32_e32 v130, 19, v117
	s_nop 0
	v_cndmask_b32_e32 v60, v215, v60, vcc
	v_cmp_lt_u32_e32 vcc, s85, v130
	v_add_u32_e32 v130, 51, v117
	s_nop 0
	v_cndmask_b32_e32 v45, v215, v45, vcc
	v_cmp_lt_u32_e32 vcc, s85, v130
	v_add_u32_e32 v130, 24, v117
	s_nop 0
	v_cndmask_b32_e32 v61, v215, v61, vcc
	v_cmp_lt_u32_e32 vcc, s85, v130
	v_add_u32_e32 v130, 56, v117
	s_nop 0
	v_cndmask_b32_e32 v46, v215, v46, vcc
	v_cmp_lt_u32_e32 vcc, s85, v130
	v_add_u32_e32 v130, 25, v117
	s_nop 0
	v_cndmask_b32_e32 v62, v215, v62, vcc
	v_cmp_lt_u32_e32 vcc, s85, v130
	v_add_u32_e32 v130, 57, v117
	s_nop 0
	v_cndmask_b32_e32 v47, v215, v47, vcc
	v_cmp_lt_u32_e32 vcc, s85, v130
	v_add_u32_e32 v130, 26, v117
	s_nop 0
	v_cndmask_b32_e32 v63, v215, v63, vcc
	v_cmp_lt_u32_e32 vcc, s85, v130
	v_add_u32_e32 v130, 58, v117
	s_nop 0
	v_cndmask_b32_e32 v48, v215, v48, vcc
	v_cmp_lt_u32_e32 vcc, s85, v130
	v_add_u32_e32 v130, 27, v117
	s_nop 0
	v_cndmask_b32_e32 v64, v215, v64, vcc
	v_cmp_lt_u32_e32 vcc, s85, v130
	v_add_u32_e32 v130, 59, v117
	s_nop 0
	v_cndmask_b32_e32 v49, v215, v49, vcc
	v_cmp_lt_u32_e32 vcc, s85, v130
	s_nop 1
	v_cndmask_b32_e32 v65, v215, v65, vcc
.LBB0_459:
	s_nop 1
	v_max3_f32 v130, v34, v35, v36
	v_max3_f32 v131, v42, v43, v44
	v_max3_f32 v250, v50, v51, v52
	v_max3_f32 v157, v58, v59, v60
	v_max3_f32 v130, v130, v37, v38
	v_max3_f32 v131, v131, v45, v46
	v_max3_f32 v250, v250, v53, v54
	v_max3_f32 v157, v157, v61, v62
	v_max3_f32 v130, v130, v39, v40
	v_max3_f32 v131, v131, v47, v48
	v_max3_f32 v250, v250, v55, v56
	v_max3_f32 v157, v157, v63, v64
	v_max3_f32 v130, v130, v131, v41
	v_max3_f32 v250, v250, v157, v57
	v_max3_f32 v130, v130, v250, v49
	v_max_f32_e32 v130, v130, v65
	ds_bpermute_b32 v131, v166, v130
	s_waitcnt lgkmcnt(0)
	v_max3_f32 v130, v116, v130, v131
	v_cmp_neq_f32_e32 vcc, v130, v116
	s_cbranch_vccz .LBB0_461
	v_sub_f32_e32 v131, v116, v130
	v_mul_f32_e32 v131, 0x3fb8aa3b, v131
	v_exp_f32_e32 v250, v131
	v_mov_b32_e32 v116, v130
	v_pk_mul_f32 v[2:3], v[2:3], v[250:251] op_sel_hi:[1,0]
	v_pk_mul_f32 v[4:5], v[4:5], v[250:251] op_sel_hi:[1,0]
	v_pk_mul_f32 v[6:7], v[6:7], v[250:251] op_sel_hi:[1,0]
	v_pk_mul_f32 v[8:9], v[8:9], v[250:251] op_sel_hi:[1,0]
	v_pk_mul_f32 v[10:11], v[10:11], v[250:251] op_sel_hi:[1,0]
	v_pk_mul_f32 v[12:13], v[12:13], v[250:251] op_sel_hi:[1,0]
	v_pk_mul_f32 v[14:15], v[14:15], v[250:251] op_sel_hi:[1,0]
	v_pk_mul_f32 v[16:17], v[16:17], v[250:251] op_sel_hi:[1,0]
	v_pk_mul_f32 v[18:19], v[18:19], v[250:251] op_sel_hi:[1,0]
	v_pk_mul_f32 v[20:21], v[20:21], v[250:251] op_sel_hi:[1,0]
	v_pk_mul_f32 v[22:23], v[22:23], v[250:251] op_sel_hi:[1,0]
	v_pk_mul_f32 v[24:25], v[24:25], v[250:251] op_sel_hi:[1,0]
	v_pk_mul_f32 v[26:27], v[26:27], v[250:251] op_sel_hi:[1,0]
	v_pk_mul_f32 v[28:29], v[28:29], v[250:251] op_sel_hi:[1,0]
	v_pk_mul_f32 v[30:31], v[30:31], v[250:251] op_sel_hi:[1,0]
	v_pk_mul_f32 v[32:33], v[32:33], v[250:251] op_sel_hi:[1,0]
	v_mul_f32_e32 v114, v114, v250
.LBB0_461:
	v_mul_f32_e32 v226, 0xbfb8aa3b, v130
	v_fma_f32 v34, v34, s74, v226
	v_fma_f32 v35, v35, s74, v226
	v_fma_f32 v36, v36, s74, v226
	v_fma_f32 v37, v37, s74, v226
	v_fma_f32 v38, v38, s74, v226
	v_fma_f32 v39, v39, s74, v226
	v_fma_f32 v40, v40, s74, v226
	v_fma_f32 v41, v41, s74, v226
	v_exp_f32_e32 v34, v34
	v_exp_f32_e32 v35, v35
	v_exp_f32_e32 v36, v36
	v_exp_f32_e32 v37, v37
	v_exp_f32_e32 v38, v38
	v_exp_f32_e32 v39, v39
	v_exp_f32_e32 v40, v40
	v_exp_f32_e32 v41, v41
	v_fma_f32 v42, v42, s74, v226
	v_fma_f32 v43, v43, s74, v226
	v_fma_f32 v44, v44, s74, v226
	v_fma_f32 v45, v45, s74, v226
	v_fma_f32 v46, v46, s74, v226
	v_fma_f32 v47, v47, s74, v226
	v_fma_f32 v48, v48, s74, v226
	v_fma_f32 v49, v49, s74, v226
	v_add_f32_e32 v194, v34, v36
	v_add_f32_e32 v195, v35, v37
	v_cvt_pk_bf16_f32 v158, v34, v35
	v_add_f32_e32 v196, v38, v40
	v_add_f32_e32 v197, v39, v41
	v_cvt_pk_bf16_f32 v159, v36, v37
	v_cvt_pk_bf16_f32 v160, v38, v39
	v_cvt_pk_bf16_f32 v161, v40, v41
	v_exp_f32_e32 v42, v42
	v_exp_f32_e32 v43, v43
	v_exp_f32_e32 v44, v44
	v_exp_f32_e32 v45, v45
	v_exp_f32_e32 v46, v46
	v_exp_f32_e32 v47, v47
	v_exp_f32_e32 v48, v48
	v_exp_f32_e32 v49, v49
	v_mfma_f32_32x32x16_bf16 v[2:17], v[96:99], v[158:161], v[2:17]
	v_mfma_f32_32x32x16_bf16 v[18:33], v[118:121], v[158:161], v[18:33]
	v_fma_f32 v50, v50, s74, v226
	v_fma_f32 v51, v51, s74, v226
	v_fma_f32 v52, v52, s74, v226
	v_fma_f32 v53, v53, s74, v226
	v_fma_f32 v54, v54, s74, v226
	v_fma_f32 v55, v55, s74, v226
	v_fma_f32 v56, v56, s74, v226
	v_fma_f32 v57, v57, s74, v226
	v_add_f32_e32 v194, v194, v42
	v_add_f32_e32 v195, v195, v43
	v_cvt_pk_bf16_f32 v162, v42, v43
	v_add_f32_e32 v196, v196, v44
	v_add_f32_e32 v197, v197, v45
	v_cvt_pk_bf16_f32 v163, v44, v45
	v_add_f32_e32 v194, v194, v46
	v_add_f32_e32 v195, v195, v47
	v_cvt_pk_bf16_f32 v164, v46, v47
	v_add_f32_e32 v196, v196, v48
	v_add_f32_e32 v197, v197, v49
	v_cvt_pk_bf16_f32 v165, v48, v49
	v_exp_f32_e32 v50, v50
	v_exp_f32_e32 v51, v51
	v_exp_f32_e32 v52, v52
	v_exp_f32_e32 v53, v53
	v_exp_f32_e32 v54, v54
	v_exp_f32_e32 v55, v55
	v_exp_f32_e32 v56, v56
	v_exp_f32_e32 v57, v57
	v_mfma_f32_32x32x16_bf16 v[2:17], v[100:103], v[162:165], v[2:17]
	v_mfma_f32_32x32x16_bf16 v[18:33], v[122:125], v[162:165], v[18:33]
	s_andn2_b64 vcc, exec, s[26:27]
	s_cbranch_vccnz .Lat_b_nostage
	s_xor_b32 s26, s39, 1
	s_mulk_i32 s26, 0x4800
	v_add_u32_e32 v130, s26, v115
	v_add_u32_e32 v0, s26, v94
	s_waitcnt vmcnt(0)
	ds_write_b128 v130, v[82:85]
	ds_write_b128 v0, v[86:89] offset:9216
	s_add_i32 s39, s29, 1
	s_cmp_ge_i32 s39, s23
	s_cbranch_scc1 .Lat_b_nostage
	s_cmp_gt_u32 s39, 7
	s_cselect_b64 vcc, -1, 0
	s_and_b64 vcc, s[24:25], vcc
	s_and_b64 vcc, vcc, exec
	s_cselect_b32 vcc_lo, s28, 0
	s_add_i32 vcc_lo, vcc_lo, s39
	s_ashr_i32 vcc_hi, vcc_lo, 31
	s_lshl_b64 s[68:69], vcc, 13
	v_lshl_add_u64 v[130:131], v[92:93], 0, s[68:69]
	s_lshl_b64 s[68:69], vcc, 7
	global_load_dwordx4 v[82:85], v[130:131], off
	v_lshl_add_u64 v[130:131], v[90:91], 0, s[68:69]
	global_load_dwordx4 v[86:89], v[130:131], off
.Lat_b_nostage:
	v_fma_f32 v58, v58, s74, v226
	v_fma_f32 v59, v59, s74, v226
	v_fma_f32 v60, v60, s74, v226
	v_fma_f32 v61, v61, s74, v226
	v_fma_f32 v62, v62, s74, v226
	v_fma_f32 v63, v63, s74, v226
	v_fma_f32 v64, v64, s74, v226
	v_fma_f32 v65, v65, s74, v226
	v_add_f32_e32 v194, v194, v50
	v_add_f32_e32 v195, v195, v51
	v_cvt_pk_bf16_f32 v186, v50, v51
	v_add_f32_e32 v196, v196, v52
	v_add_f32_e32 v197, v197, v53
	v_cvt_pk_bf16_f32 v187, v52, v53
	v_add_f32_e32 v194, v194, v54
	v_add_f32_e32 v195, v195, v55
	v_cvt_pk_bf16_f32 v188, v54, v55
	v_add_f32_e32 v196, v196, v56
	v_add_f32_e32 v197, v197, v57
	v_cvt_pk_bf16_f32 v189, v56, v57
	v_exp_f32_e32 v58, v58
	v_exp_f32_e32 v59, v59
	v_exp_f32_e32 v60, v60
	v_exp_f32_e32 v61, v61
	v_exp_f32_e32 v62, v62
	v_exp_f32_e32 v63, v63
	v_exp_f32_e32 v64, v64
	v_exp_f32_e32 v65, v65
	v_mfma_f32_32x32x16_bf16 v[2:17], v[104:107], v[186:189], v[2:17]
	v_mfma_f32_32x32x16_bf16 v[18:33], v[126:129], v[186:189], v[18:33]
	v_add_f32_e32 v194, v194, v58
	v_add_f32_e32 v195, v195, v59
	v_cvt_pk_bf16_f32 v190, v58, v59
	v_add_f32_e32 v196, v196, v60
	v_add_f32_e32 v197, v197, v61
	v_cvt_pk_bf16_f32 v191, v60, v61
	v_add_f32_e32 v194, v194, v62
	v_add_f32_e32 v195, v195, v63
	v_cvt_pk_bf16_f32 v192, v62, v63
	v_add_f32_e32 v196, v196, v64
	v_add_f32_e32 v197, v197, v65
	v_cvt_pk_bf16_f32 v193, v64, v65
	v_add_u32_e32 v117, 64, v117
	v_add_f32_e32 v194, v194, v196
	v_add_f32_e32 v195, v195, v197
	s_nop 0
	v_mfma_f32_32x32x16_bf16 v[2:17], v[108:111], v[190:193], v[2:17]
	v_mfma_f32_32x32x16_bf16 v[18:33], v[246:249], v[190:193], v[18:33]
	v_add_f32_e32 v0, v194, v195
	v_add_f32_e32 v114, v0, v114
.LBB0_463:
	s_waitcnt lgkmcnt(0)
	s_barrier
	s_cmp_lg_u32 s23, s29
	s_cbranch_scc0 .LBB0_467
	s_mov_b32 s80, s29
	s_branch .LBB0_455

.LBB0_470:
	s_cmp_lg_u32 s25, 0
	s_cbranch_scc1 .Lat_a_noload
	v_add_co_u32_e32 v6, vcc, 0x2000, v164
	v_lshl_add_u64 v[226:227], v[160:161], 0, s[8:9]
	s_nop 0
	v_addc_co_u32_e32 v7, vcc, 0, v165, vcc
	v_lshl_add_u64 v[14:15], v[162:163], 0, s[8:9]
	global_load_dwordx4 v[2:5], v[164:165], off
	global_load_dwordx4 v[128:131], v[14:15], off offset:128
	global_load_dwordx4 v[6:9], v[6:7], off
	global_load_dwordx4 v[10:13], v[226:227], off
	v_lshl_add_u64 v[160:161], v[160:161], 0, s[10:11]
	v_lshl_add_u64 v[162:163], v[162:163], 0, s[10:11]
	v_lshl_add_u64 v[164:165], v[164:165], 0, s[76:77]
.Lat_a_noload:
	s_and_b32 s20, s25, 1
	s_mul_i32 s21, s20, 0x8c00
	v_add_u32_e32 v0, s21, v157
	v_add3_u32 v0, v0, v151, v172
	v_add3_u32 v14, s21, v153, v151
	ds_read_b128 v[186:189], v0
	ds_read_b128 v[230:233], v0 offset:8704
	ds_read_b128 v[190:193], v0 offset:32
	ds_read_b128 v[234:237], v0 offset:8736
	ds_read_b128 v[194:197], v0 offset:64
	ds_read_b128 v[238:241], v0 offset:8768
	ds_read_b128 v[198:201], v0 offset:96
	ds_read_b128 v[242:245], v0 offset:8800
	s_waitcnt lgkmcnt(7)
	v_mfma_f32_32x32x16_bf16 v[80:95], v[186:189], v[124:127], 0
	s_waitcnt lgkmcnt(6)
	v_mfma_f32_32x32x16_bf16 v[96:111], v[230:233], v[124:127], 0
	s_waitcnt lgkmcnt(5)
	v_mfma_f32_32x32x16_bf16 v[80:95], v[190:193], v[120:123], v[80:95]
	s_waitcnt lgkmcnt(4)
	v_mfma_f32_32x32x16_bf16 v[96:111], v[234:237], v[120:123], v[96:111]
	s_waitcnt lgkmcnt(3)
	v_mfma_f32_32x32x16_bf16 v[80:95], v[194:197], v[116:119], v[80:95]
	s_waitcnt lgkmcnt(2)
	v_mfma_f32_32x32x16_bf16 v[96:111], v[238:241], v[116:119], v[96:111]
	s_waitcnt lgkmcnt(1)
	v_mfma_f32_32x32x16_bf16 v[80:95], v[198:201], v[112:115], v[80:95]
	s_waitcnt lgkmcnt(0)
	v_mfma_f32_32x32x16_bf16 v[96:111], v[242:245], v[112:115], v[96:111]
	ds_read_b128 v[186:189], v14 offset:17408
	ds_read_b128 v[230:233], v14 offset:22016
	ds_read_b128 v[190:193], v14 offset:26624
	ds_read_b128 v[234:237], v14 offset:31232
	ds_read_b128 v[194:197], v14 offset:17440
	ds_read_b128 v[238:241], v14 offset:22048
	ds_read_b128 v[198:201], v14 offset:26656
	ds_read_b128 v[242:245], v14 offset:31264
	s_nop 3
	v_max3_f32 v246, v80, v81, v82
	v_max3_f32 v247, v88, v89, v90
	v_max3_f32 v248, v96, v97, v98
	v_max3_f32 v249, v104, v105, v106
	v_max3_f32 v246, v246, v83, v84
	v_max3_f32 v247, v247, v91, v92
	v_max3_f32 v248, v248, v99, v100
	v_max3_f32 v249, v249, v107, v108
	v_max3_f32 v246, v246, v85, v86
	v_max3_f32 v247, v247, v93, v94
	v_max3_f32 v248, v248, v101, v102
	v_max3_f32 v249, v249, v109, v110
	v_max3_f32 v246, v246, v247, v87
	v_max3_f32 v248, v248, v249, v103
	v_max3_f32 v246, v246, v248, v95
	v_max_f32_e32 v246, v246, v111
	ds_bpermute_b32 v247, v166, v246
	s_waitcnt lgkmcnt(0)
	v_max3_f32 v246, v159, v246, v247
	v_cmp_neq_f32_e32 vcc, v246, v159
	s_cbranch_vccz .Lat_a_norescale
	v_sub_f32_e32 v247, v159, v246
	v_mul_f32_e32 v247, 0x3fb8aa3b, v247
	v_exp_f32_e32 v250, v247
	v_mov_b32_e32 v159, v246
	v_pk_mul_f32 v[16:17], v[16:17], v[250:251] op_sel_hi:[1,0]
	v_pk_mul_f32 v[18:19], v[18:19], v[250:251] op_sel_hi:[1,0]
	v_pk_mul_f32 v[20:21], v[20:21], v[250:251] op_sel_hi:[1,0]
	v_pk_mul_f32 v[22:23], v[22:23], v[250:251] op_sel_hi:[1,0]
	v_pk_mul_f32 v[24:25], v[24:25], v[250:251] op_sel_hi:[1,0]
	v_pk_mul_f32 v[26:27], v[26:27], v[250:251] op_sel_hi:[1,0]
	v_pk_mul_f32 v[28:29], v[28:29], v[250:251] op_sel_hi:[1,0]
	v_pk_mul_f32 v[30:31], v[30:31], v[250:251] op_sel_hi:[1,0]
	v_pk_mul_f32 v[32:33], v[32:33], v[250:251] op_sel_hi:[1,0]
	v_pk_mul_f32 v[34:35], v[34:35], v[250:251] op_sel_hi:[1,0]
	v_pk_mul_f32 v[36:37], v[36:37], v[250:251] op_sel_hi:[1,0]
	v_pk_mul_f32 v[38:39], v[38:39], v[250:251] op_sel_hi:[1,0]
	v_pk_mul_f32 v[40:41], v[40:41], v[250:251] op_sel_hi:[1,0]
	v_pk_mul_f32 v[42:43], v[42:43], v[250:251] op_sel_hi:[1,0]
	v_pk_mul_f32 v[44:45], v[44:45], v[250:251] op_sel_hi:[1,0]
	v_pk_mul_f32 v[46:47], v[46:47], v[250:251] op_sel_hi:[1,0]
	v_pk_mul_f32 v[48:49], v[48:49], v[250:251] op_sel_hi:[1,0]
	v_pk_mul_f32 v[50:51], v[50:51], v[250:251] op_sel_hi:[1,0]
	v_pk_mul_f32 v[52:53], v[52:53], v[250:251] op_sel_hi:[1,0]
	v_pk_mul_f32 v[54:55], v[54:55], v[250:251] op_sel_hi:[1,0]
	v_pk_mul_f32 v[56:57], v[56:57], v[250:251] op_sel_hi:[1,0]
	v_pk_mul_f32 v[58:59], v[58:59], v[250:251] op_sel_hi:[1,0]
	v_pk_mul_f32 v[60:61], v[60:61], v[250:251] op_sel_hi:[1,0]
	v_pk_mul_f32 v[62:63], v[62:63], v[250:251] op_sel_hi:[1,0]
	v_pk_mul_f32 v[64:65], v[64:65], v[250:251] op_sel_hi:[1,0]
	v_pk_mul_f32 v[66:67], v[66:67], v[250:251] op_sel_hi:[1,0]
	v_pk_mul_f32 v[68:69], v[68:69], v[250:251] op_sel_hi:[1,0]
	v_pk_mul_f32 v[70:71], v[70:71], v[250:251] op_sel_hi:[1,0]
	v_pk_mul_f32 v[72:73], v[72:73], v[250:251] op_sel_hi:[1,0]
	v_pk_mul_f32 v[74:75], v[74:75], v[250:251] op_sel_hi:[1,0]
	v_pk_mul_f32 v[76:77], v[76:77], v[250:251] op_sel_hi:[1,0]
	v_pk_mul_f32 v[78:79], v[78:79], v[250:251] op_sel_hi:[1,0]
	v_mul_f32_e32 v149, v149, v250
.Lat_a_norescale:
	v_mul_f32_e32 v250, 0xbfb8aa3b, v246
	v_fma_f32 v80, v80, s74, v250
	v_fma_f32 v81, v81, s74, v250
	v_fma_f32 v82, v82, s74, v250
	v_fma_f32 v83, v83, s74, v250
	v_fma_f32 v84, v84, s74, v250
	v_fma_f32 v85, v85, s74, v250
	v_fma_f32 v86, v86, s74, v250
	v_fma_f32 v87, v87, s74, v250
	v_exp_f32_e32 v80, v80
	v_exp_f32_e32 v81, v81
	v_exp_f32_e32 v82, v82
	v_exp_f32_e32 v83, v83
	v_exp_f32_e32 v84, v84
	v_exp_f32_e32 v85, v85
	v_exp_f32_e32 v86, v86
	v_exp_f32_e32 v87, v87
	v_fma_f32 v88, v88, s74, v250
	v_fma_f32 v89, v89, s74, v250
	v_fma_f32 v90, v90, s74, v250
	v_fma_f32 v91, v91, s74, v250
	v_fma_f32 v92, v92, s74, v250
	v_fma_f32 v93, v93, s74, v250
	v_fma_f32 v94, v94, s74, v250
	v_fma_f32 v95, v95, s74, v250
	v_add_f32_e32 v248, v80, v82
	v_add_f32_e32 v249, v81, v83
	v_add_f32_e32 v226, v84, v86
	v_add_f32_e32 v227, v85, v87
	v_cvt_pk_bf16_f32 v80, v80, v81
	v_cvt_pk_bf16_f32 v81, v82, v83
	v_cvt_pk_bf16_f32 v82, v84, v85
	v_cvt_pk_bf16_f32 v83, v86, v87
	v_exp_f32_e32 v88, v88
	v_exp_f32_e32 v89, v89
	v_exp_f32_e32 v90, v90
	v_exp_f32_e32 v91, v91
	v_exp_f32_e32 v92, v92
	v_exp_f32_e32 v93, v93
	v_exp_f32_e32 v94, v94
	v_exp_f32_e32 v95, v95
	v_mfma_f32_32x32x16_bf16 v[64:79], v[186:189], v[80:83], v[64:79]
	ds_read_b128 v[186:189], v14 offset:17472
	v_mfma_f32_32x32x16_bf16 v[48:63], v[230:233], v[80:83], v[48:63]
	ds_read_b128 v[230:233], v14 offset:22080
	v_mfma_f32_32x32x16_bf16 v[32:47], v[190:193], v[80:83], v[32:47]
	ds_read_b128 v[190:193], v14 offset:26688
	v_mfma_f32_32x32x16_bf16 v[16:31], v[234:237], v[80:83], v[16:31]
	ds_read_b128 v[234:237], v14 offset:31296
	v_fma_f32 v96, v96, s74, v250
	v_fma_f32 v97, v97, s74, v250
	v_fma_f32 v98, v98, s74, v250
	v_fma_f32 v99, v99, s74, v250
	v_fma_f32 v100, v100, s74, v250
	v_fma_f32 v101, v101, s74, v250
	v_fma_f32 v102, v102, s74, v250
	v_fma_f32 v103, v103, s74, v250
	v_add_f32_e32 v248, v248, v88
	v_add_f32_e32 v249, v249, v89
	v_cvt_pk_bf16_f32 v88, v88, v89
	v_add_f32_e32 v226, v226, v90
	v_add_f32_e32 v227, v227, v91
	v_cvt_pk_bf16_f32 v89, v90, v91
	v_add_f32_e32 v248, v248, v92
	v_add_f32_e32 v249, v249, v93
	v_cvt_pk_bf16_f32 v90, v92, v93
	v_add_f32_e32 v226, v226, v94
	v_add_f32_e32 v227, v227, v95
	v_cvt_pk_bf16_f32 v91, v94, v95
	v_exp_f32_e32 v96, v96
	v_exp_f32_e32 v97, v97
	v_exp_f32_e32 v98, v98
	v_exp_f32_e32 v99, v99
	v_exp_f32_e32 v100, v100
	v_exp_f32_e32 v101, v101
	v_exp_f32_e32 v102, v102
	v_exp_f32_e32 v103, v103
	v_mfma_f32_32x32x16_bf16 v[64:79], v[194:197], v[88:91], v[64:79]
	ds_read_b128 v[194:197], v14 offset:17504
	v_mfma_f32_32x32x16_bf16 v[48:63], v[238:241], v[88:91], v[48:63]
	ds_read_b128 v[238:241], v14 offset:22112
	v_mfma_f32_32x32x16_bf16 v[32:47], v[198:201], v[88:91], v[32:47]
	ds_read_b128 v[198:201], v14 offset:26720
	v_mfma_f32_32x32x16_bf16 v[16:31], v[242:245], v[88:91], v[16:31]
	ds_read_b128 v[242:245], v14 offset:31328
	s_cmp_lt_u32 s25, s26
	s_cbranch_scc0 .Lat_a_nostage
	s_xor_b32 s22, s20, 1
	s_mul_i32 s22, s22, 0x8c00
	v_add_u32_e32 v0, s22, v155
	v_add_u32_e32 v14, s22, v158
	s_waitcnt vmcnt(0)
	ds_write_b128 v0, v[2:5]
	ds_write_b128 v0, v[6:9] offset:8704
	ds_write_b128 v14, v[10:13] offset:17408
	ds_write_b128 v14, v[128:131] offset:26624
	s_add_i32 s22, s25, 2
	s_cmp_le_u32 s22, s26
	s_cbranch_scc0 .Lat_a_nostage
	v_add_co_u32_e32 v6, vcc, 0x2000, v164
	v_lshl_add_u64 v[10:11], v[160:161], 0, s[8:9]
	s_nop 0
	v_addc_co_u32_e32 v7, vcc, 0, v165, vcc
	v_lshl_add_u64 v[14:15], v[162:163], 0, s[8:9]
	global_load_dwordx4 v[2:5], v[164:165], off
	global_load_dwordx4 v[128:131], v[14:15], off offset:128
	global_load_dwordx4 v[6:9], v[6:7], off
	global_load_dwordx4 v[10:13], v[10:11], off
	v_lshl_add_u64 v[160:161], v[160:161], 0, s[10:11]
	v_lshl_add_u64 v[162:163], v[162:163], 0, s[10:11]
	v_lshl_add_u64 v[164:165], v[164:165], 0, s[76:77]
.Lat_a_nostage:
	v_fma_f32 v104, v104, s74, v250
	v_fma_f32 v105, v105, s74, v250
	v_fma_f32 v106, v106, s74, v250
	v_fma_f32 v107, v107, s74, v250
	v_fma_f32 v108, v108, s74, v250
	v_fma_f32 v109, v109, s74, v250
	v_fma_f32 v110, v110, s74, v250
	v_fma_f32 v111, v111, s74, v250
	v_add_f32_e32 v248, v248, v96
	v_add_f32_e32 v249, v249, v97
	v_cvt_pk_bf16_f32 v96, v96, v97
	v_add_f32_e32 v226, v226, v98
	v_add_f32_e32 v227, v227, v99
	v_cvt_pk_bf16_f32 v97, v98, v99
	v_add_f32_e32 v248, v248, v100
	v_add_f32_e32 v249, v249, v101
	v_cvt_pk_bf16_f32 v98, v100, v101
	v_add_f32_e32 v226, v226, v102
	v_add_f32_e32 v227, v227, v103
	v_cvt_pk_bf16_f32 v99, v102, v103
	v_exp_f32_e32 v104, v104
	v_exp_f32_e32 v105, v105
	v_exp_f32_e32 v106, v106
	v_exp_f32_e32 v107, v107
	v_exp_f32_e32 v108, v108
	v_exp_f32_e32 v109, v109
	v_exp_f32_e32 v110, v110
	v_exp_f32_e32 v111, v111
	s_waitcnt lgkmcnt(4)
	v_mfma_f32_32x32x16_bf16 v[64:79], v[186:189], v[96:99], v[64:79]
	v_mfma_f32_32x32x16_bf16 v[48:63], v[230:233], v[96:99], v[48:63]
	v_mfma_f32_32x32x16_bf16 v[32:47], v[190:193], v[96:99], v[32:47]
	v_mfma_f32_32x32x16_bf16 v[16:31], v[234:237], v[96:99], v[16:31]
	v_add_f32_e32 v248, v248, v104
	v_add_f32_e32 v249, v249, v105
	v_cvt_pk_bf16_f32 v104, v104, v105
	v_add_f32_e32 v226, v226, v106
	v_add_f32_e32 v227, v227, v107
	v_cvt_pk_bf16_f32 v105, v106, v107
	v_add_f32_e32 v248, v248, v108
	v_add_f32_e32 v249, v249, v109
	v_cvt_pk_bf16_f32 v106, v108, v109
	v_add_f32_e32 v226, v226, v110
	v_add_f32_e32 v227, v227, v111
	v_cvt_pk_bf16_f32 v107, v110, v111
	v_add_f32_e32 v248, v248, v226
	v_add_f32_e32 v249, v249, v227
	s_waitcnt lgkmcnt(0)
	s_cmp_lt_u32 s25, s26
	v_mfma_f32_32x32x16_bf16 v[64:79], v[194:197], v[104:107], v[64:79]
	v_mfma_f32_32x32x16_bf16 v[48:63], v[238:241], v[104:107], v[48:63]
	v_mfma_f32_32x32x16_bf16 v[32:47], v[198:201], v[104:107], v[32:47]
	v_mfma_f32_32x32x16_bf16 v[16:31], v[242:245], v[104:107], v[16:31]
	v_add_f32_e32 v0, v248, v249
	v_add_f32_e32 v149, v0, v149
.Lat_a_nowrite:
	s_waitcnt lgkmcnt(0)
	s_barrier
	s_add_i32 s25, s25, 1
	s_cmp_le_u32 s25, s26
	s_cbranch_scc1 .LBB0_470
	v_mov_b32_e32 v0, v149
	ds_bpermute_b32 v2, v166, v0
	s_waitcnt lgkmcnt(0)
	v_add_f32_e32 v0, v0, v2
	v_div_scale_f32 v2, s[20:21], v0, v0, 1.0
	v_rcp_f32_e32 v3, v2
	s_nop 0
	v_fma_f32 v4, -v2, v3, 1.0
	v_fmac_f32_e32 v3, v4, v3
	v_div_scale_f32 v4, vcc, 1.0, v0, 1.0
	v_mul_f32_e32 v5, v4, v3
	v_fma_f32 v6, -v2, v5, v4
	v_fmac_f32_e32 v5, v6, v3
	v_fma_f32 v2, -v2, v5, v4
	v_div_fmas_f32 v2, v2, v3, v5
	v_div_fixup_f32 v0, v2, v0, 1.0
	v_pk_mul_f32 v[88:89], v[64:65], v[0:1] op_sel_hi:[1,0]
	v_pk_mul_f32 v[92:93], v[66:67], v[0:1] op_sel_hi:[1,0]
	v_pk_mul_f32 v[4:5], v[68:69], v[0:1] op_sel_hi:[1,0]
	v_pk_mul_f32 v[90:91], v[70:71], v[0:1] op_sel_hi:[1,0]
	v_pk_mul_f32 v[2:3], v[72:73], v[0:1] op_sel_hi:[1,0]
	v_pk_mul_f32 v[86:87], v[74:75], v[0:1] op_sel_hi:[1,0]
	v_pk_mul_f32 v[10:11], v[76:77], v[0:1] op_sel_hi:[1,0]
	v_pk_mul_f32 v[84:85], v[78:79], v[0:1] op_sel_hi:[1,0]
	v_pk_mul_f32 v[6:7], v[48:49], v[0:1] op_sel_hi:[1,0]
	v_pk_mul_f32 v[12:13], v[50:51], v[0:1] op_sel_hi:[1,0]
	v_pk_mul_f32 v[48:49], v[52:53], v[0:1] op_sel_hi:[1,0]
	v_pk_mul_f32 v[8:9], v[54:55], v[0:1] op_sel_hi:[1,0]
	v_pk_mul_f32 v[14:15], v[56:57], v[0:1] op_sel_hi:[1,0]
	v_pk_mul_f32 v[72:73], v[58:59], v[0:1] op_sel_hi:[1,0]
	v_pk_mul_f32 v[64:65], v[60:61], v[0:1] op_sel_hi:[1,0]
	v_pk_mul_f32 v[54:55], v[62:63], v[0:1] op_sel_hi:[1,0]
	v_pk_mul_f32 v[70:71], v[32:33], v[0:1] op_sel_hi:[1,0]
	v_pk_mul_f32 v[78:79], v[34:35], v[0:1] op_sel_hi:[1,0]
	v_pk_mul_f32 v[74:75], v[36:37], v[0:1] op_sel_hi:[1,0]
	v_pk_mul_f32 v[82:83], v[38:39], v[0:1] op_sel_hi:[1,0]
	v_pk_mul_f32 v[68:69], v[40:41], v[0:1] op_sel_hi:[1,0]
	v_pk_mul_f32 v[80:81], v[42:43], v[0:1] op_sel_hi:[1,0]
	v_pk_mul_f32 v[60:61], v[44:45], v[0:1] op_sel_hi:[1,0]
	v_pk_mul_f32 v[76:77], v[46:47], v[0:1] op_sel_hi:[1,0]
	v_pk_mul_f32 v[50:51], v[16:17], v[0:1] op_sel_hi:[1,0]
	v_pk_mul_f32 v[66:67], v[18:19], v[0:1] op_sel_hi:[1,0]
	v_pk_mul_f32 v[42:43], v[20:21], v[0:1] op_sel_hi:[1,0]
	v_pk_mul_f32 v[56:57], v[22:23], v[0:1] op_sel_hi:[1,0]
	v_pk_mul_f32 v[38:39], v[24:25], v[0:1] op_sel_hi:[1,0]
	v_pk_mul_f32 v[52:53], v[26:27], v[0:1] op_sel_hi:[1,0]
	v_pk_mul_f32 v[18:19], v[28:29], v[0:1] op_sel_hi:[1,0]
	v_pk_mul_f32 v[16:17], v[30:31], v[0:1] op_sel_hi:[1,0]
	s_and_saveexec_b64 s[20:21], s[42:43]
	s_cbranch_execz .LBB0_476
	ds_write2st64_b32 v173, v88, v89 offset1:1
	ds_write2st64_b32 v173, v92, v93 offset0:2 offset1:3
	ds_write2st64_b32 v173, v4, v5 offset0:4 offset1:5
	ds_write2st64_b32 v173, v90, v91 offset0:6 offset1:7
	ds_write2st64_b32 v173, v2, v3 offset0:8 offset1:9
	ds_write2st64_b32 v173, v86, v87 offset0:10 offset1:11
	ds_write2st64_b32 v173, v10, v11 offset0:12 offset1:13
	ds_write2st64_b32 v173, v84, v85 offset0:14 offset1:15
	ds_write2st64_b32 v173, v6, v7 offset0:16 offset1:17
	ds_write2st64_b32 v173, v12, v13 offset0:18 offset1:19
	ds_write2st64_b32 v173, v48, v49 offset0:20 offset1:21
	ds_write2st64_b32 v173, v8, v9 offset0:22 offset1:23
	ds_write2st64_b32 v173, v14, v15 offset0:24 offset1:25
	ds_write2st64_b32 v173, v72, v73 offset0:26 offset1:27
	ds_write2st64_b32 v173, v64, v65 offset0:28 offset1:29
	ds_write2st64_b32 v173, v54, v55 offset0:30 offset1:31
	ds_write2st64_b32 v173, v70, v71 offset0:32 offset1:33
	ds_write2st64_b32 v173, v78, v79 offset0:34 offset1:35
	ds_write2st64_b32 v173, v74, v75 offset0:36 offset1:37
	ds_write2st64_b32 v173, v82, v83 offset0:38 offset1:39
	ds_write2st64_b32 v173, v68, v69 offset0:40 offset1:41
	ds_write2st64_b32 v173, v80, v81 offset0:42 offset1:43
	ds_write2st64_b32 v173, v60, v61 offset0:44 offset1:45
	ds_write2st64_b32 v173, v76, v77 offset0:46 offset1:47
	ds_write2st64_b32 v173, v50, v51 offset0:48 offset1:49
	ds_write2st64_b32 v173, v66, v67 offset0:50 offset1:51
	ds_write2st64_b32 v173, v42, v43 offset0:52 offset1:53
	ds_write2st64_b32 v173, v56, v57 offset0:54 offset1:55
	ds_write2st64_b32 v173, v38, v39 offset0:56 offset1:57
	ds_write2st64_b32 v173, v52, v53 offset0:58 offset1:59
	ds_write2st64_b32 v173, v18, v19 offset0:60 offset1:61
	ds_write2st64_b32 v173, v16, v17 offset0:62 offset1:63
